# final candidate: v38 plus one restored wait state in the S5-GEMM epilogue (MFMA SrcC write-after-read distance)
# speedup vs baseline: 1.0112x; 1.0076x over previous
; DI f32x4 mfma16(bf16x8 a, bf16x8 b, f32x4 c) { return __builtin_amdgcn_mfma_f32_16x16x32_bf16(a, b, c, 0, 0, 0); }
; template <class LA, class LB>
; DI void gemm_tile(unsigned char* smem, const int tid, int nk, LA la, LB lb, f32x4 (&acc)[4][4]) {
;     ...
;         const unsigned char* cA = sA + cur * 16384 + (wf * 64 + frow) * 128;
;         const unsigned char* cB = sB + cur * 16384 + (wt * 64 + frow) * 128;
; #pragma unroll
;         for (int ks = 0; ks < 2; ++ks) {
;             const int ch = ((ks * 4 + fq) ^ fsw) << 4;
;             bf16x8 af[4], bfr[4];
; #pragma unroll
;             for (int i = 0; i < 4; ++i) { af[i] = *(const bf16x8*)(cA + i * 2048 + ch); bfr[i] = *(const bf16x8*)(cB + i * 2048 + ch); }
; #pragma unroll
;             for (int i = 0; i < 4; ++i)
; #pragma unroll
;                 for (int j = 0; j < 4; ++j) acc[i][j] = mfma16(af[i], bfr[j], acc[i][j]);
;         }
;         if (kt + 1 < nk) {
;             const int nbuf = (cur ^ 1) * 16384;
; #pragma unroll
;             for (int i = 0; i < 4; ++i) { *(uint4*)(sA + nbuf + woff + i * 4096) = ra[i]; *(uint4*)(sB + nbuf + woff + i * 4096) = rb[i]; }
;         }
;         __syncthreads();
; DI void phase5(const Params& p, unsigned char* smem, const int tid, const int vb, const int nvb) {
;     ...
;             uint2 uu = *(const uint2*)(us + (((size_t)g * 512 + n) * 64 + t) * 16 + c);
;             float4 dd = *(const float4*)(dsk + ch);
.LBB0_526:
	s_or_b64 exec, exec, s[24:25]
	v_readlane_b32 s36, v254, 26
	v_readlane_b32 s37, v254, 27
	v_or_b32_e32 v200, v199, v193
	v_or_b32_e32 v248, v198, v188
	v_lshlrev_b32_e32 v200, 11, v200
	v_lshl_add_u32 v200, v248, 1, v200
	v_lshl_add_u32 v200, v144, 1, v200
	v_mov_b32_e32 v201, 0
	v_lshl_or_b32 v246, v152, 4, v144
	v_ashrrev_i32_e32 v247, 31, v246
	s_mov_b64 s[34:35], 0x8000
	v_lshl_add_u64 v[246:247], v[246:247], 2, s[36:37]
	v_lshl_add_u64 v[202:203], v[150:151], 0, v[200:201]
	v_lshl_add_u64 v[204:205], v[202:203], 0, s[34:35]
	v_lshl_add_u64 v[206:207], v[204:205], 0, s[34:35]
	v_lshl_add_u64 v[208:209], v[206:207], 0, s[34:35]
	global_load_dwordx4 v[242:245], v[246:247], off
	global_load_dwordx2 v[210:211], v[202:203], off
	global_load_dwordx2 v[212:213], v[204:205], off
	global_load_dwordx2 v[214:215], v[206:207], off
	global_load_dwordx2 v[216:217], v[208:209], off
	global_load_dwordx2 v[218:219], v[202:203], off offset:32
	global_load_dwordx2 v[220:221], v[204:205], off offset:32
	global_load_dwordx2 v[222:223], v[206:207], off offset:32
	global_load_dwordx2 v[224:225], v[208:209], off offset:32
	global_load_dwordx2 v[226:227], v[202:203], off offset:64
	global_load_dwordx2 v[228:229], v[204:205], off offset:64
	global_load_dwordx2 v[230:231], v[206:207], off offset:64
	global_load_dwordx2 v[232:233], v[208:209], off offset:64
	global_load_dwordx2 v[234:235], v[202:203], off offset:96
	global_load_dwordx2 v[236:237], v[204:205], off offset:96
	global_load_dwordx2 v[238:239], v[206:207], off offset:96
	global_load_dwordx2 v[240:241], v[208:209], off offset:96
	v_add_u32_e32 v28, v189, v191
	v_add_u32_e32 v32, v190, v191
	ds_read_b128 v[0:3], v28
	ds_read_b128 v[4:7], v32 offset:32768
	ds_read_b128 v[8:11], v28 offset:2048
	ds_read_b128 v[12:15], v32 offset:34816
	ds_read_b128 v[16:19], v28 offset:4096
	ds_read_b128 v[20:23], v32 offset:36864
	ds_read_b128 v[28:31], v28 offset:6144
	ds_read_b128 v[32:35], v32 offset:38912
	s_waitcnt lgkmcnt(6)
	v_mfma_f32_16x16x32_bf16 v[40:43], v[0:3], v[4:7], v[40:43]
	v_readlane_b32 s16, v254, 20
	v_readlane_b32 s22, v254, 26
	v_readlane_b32 s23, v254, 27
	s_waitcnt lgkmcnt(4)
	v_mfma_f32_16x16x32_bf16 v[44:47], v[0:3], v[12:15], v[44:47]
	v_add_u32_e32 v197, s90, v197
	v_cmp_lt_i32_e32 vcc, s40, v197
	v_add_u32_e32 v194, s38, v194
	s_waitcnt lgkmcnt(2)
	v_mfma_f32_16x16x32_bf16 v[48:51], v[0:3], v[20:23], v[48:51]
	s_or_b64 s[14:15], vcc, s[14:15]
	v_readlane_b32 s17, v254, 21
	v_readlane_b32 s18, v254, 22
	s_waitcnt lgkmcnt(0)
	v_mfma_f32_16x16x32_bf16 v[0:3], v[0:3], v[32:35], v[56:59]
	v_readlane_b32 s19, v254, 23
	v_readlane_b32 s20, v254, 24
	v_readlane_b32 s21, v254, 25
	v_mfma_f32_16x16x32_bf16 v[56:59], v[8:11], v[4:7], v[80:83]
	v_readlane_b32 s24, v254, 28
	v_readlane_b32 s25, v254, 29
	v_readlane_b32 s26, v254, 30
	v_mfma_f32_16x16x32_bf16 v[76:79], v[8:11], v[12:15], v[76:79]
	v_readlane_b32 s27, v254, 31
	v_readlane_b32 s28, v254, 32
	v_readlane_b32 s29, v254, 33
	v_mfma_f32_16x16x32_bf16 v[68:71], v[8:11], v[20:23], v[68:71]
	v_readlane_b32 s30, v254, 34
	v_readlane_b32 s31, v254, 35
	v_mfma_f32_16x16x32_bf16 v[8:11], v[8:11], v[32:35], v[64:67]
	v_mfma_f32_16x16x32_bf16 v[64:67], v[16:19], v[4:7], v[84:87]
	v_mfma_f32_16x16x32_bf16 v[72:75], v[16:19], v[12:15], v[72:75]
	v_mfma_f32_16x16x32_bf16 v[24:27], v[16:19], v[20:23], v[24:27]
	v_mfma_f32_16x16x32_bf16 v[4:7], v[28:31], v[4:7], v[104:107]
	v_mfma_f32_16x16x32_bf16 v[12:15], v[28:31], v[12:15], v[108:111]
	v_mfma_f32_16x16x32_bf16 v[20:23], v[28:31], v[20:23], v[112:115]
	v_mfma_f32_16x16x32_bf16 v[28:31], v[28:31], v[32:35], v[116:119]
	s_nop 1
	v_add_u32_e32 v112, v189, v192
	v_add_u32_e32 v116, v190, v192
	v_mfma_f32_16x16x32_bf16 v[16:19], v[16:19], v[32:35], v[100:103]
	ds_read_b128 v[32:35], v112
	ds_read_b128 v[80:83], v116 offset:32768
	ds_read_b128 v[84:87], v112 offset:2048
	ds_read_b128 v[100:103], v116 offset:34816
	ds_read_b128 v[104:107], v112 offset:4096
	ds_read_b128 v[108:111], v116 offset:36864
	ds_read_b128 v[112:115], v112 offset:6144
	ds_read_b128 v[116:119], v116 offset:38912
	ds_write_b128 v187, v[36:39] offset:16384
	ds_write_b128 v187, v[52:55] offset:49152
	ds_write_b128 v187, v[60:63] offset:20480
	ds_write_b128 v187, v[88:91] offset:53248
	ds_write_b128 v187, v[92:95] offset:24576
	ds_write_b128 v187, v[96:99] offset:57344
	ds_write_b128 v187, v[120:123] offset:28672
	ds_write_b128 v187, v[124:127] offset:61440
	v_add_u32_e32 v96, 0x4000, v189
	v_add_u32_e32 v97, 0x4000, v190
	v_add_u32_e32 v88, v96, v191
	v_add_u32_e32 v92, v97, v191
	s_waitcnt lgkmcnt(14)
	v_mfma_f32_16x16x32_bf16 v[40:43], v[32:35], v[80:83], v[40:43]
	s_waitcnt lgkmcnt(0)
	s_barrier
; DI float bf2f(unsigned short h) { return __uint_as_float(((unsigned)h) << 16); }
; DI uint2 pk4(f32x4 v) { return make_uint2(pk2(v[0], v[1]), pk2(v[2], v[3])); }
; DI float gelu_t(float x) { float u = 1.5957691216057308f * (x + 0.044715f * x * x * x); return x * __builtin_amdgcn_rcpf(1.f + __expf(-u)); }
; DI f32x4 mfma16(bf16x8 a, bf16x8 b, f32x4 c) { return __builtin_amdgcn_mfma_f32_16x16x32_bf16(a, b, c, 0, 0, 0); }
; template <class LA, class LB>
; DI void gemm_tile(unsigned char* smem, const int tid, int nk, LA la, LB lb, f32x4 (&acc)[4][4]) {
;     ...
;             for (int i = 0; i < 4; ++i) { af[i] = *(const bf16x8*)(cA + i * 2048 + ch); bfr[i] = *(const bf16x8*)(cB + i * 2048 + ch); }
; #pragma unroll
;             for (int i = 0; i < 4; ++i)
; #pragma unroll
;                 for (int j = 0; j < 4; ++j) acc[i][j] = mfma16(af[i], bfr[j], acc[i][j]);
; DI void phase5(const Params& p, unsigned char* smem, const int tid, const int vb, const int nvb) {
;     ...
;         epi_loop(acc, tid, [&](const int epi_f, const int epi_t, const f32x4 accv) __attribute__((always_inline)) {
;             const int m = mt * 128 + epi_f, n = nt * 128 + epi_t;
;             const int t = m >> 4, c = m & 15;
;             const size_t tok = (size_t)n * 64 + t;
;             const int ch = g * 16 + c;
;             uint2 uu = *(const uint2*)(us + (((size_t)g * 512 + n) * 64 + t) * 16 + c);
;             float4 dd = *(const float4*)(dsk + ch);
;             f32x4 v = accv;
;             v[0] = gelu_t(v[0] + dd.x * bf2f(uu.x & 0xffff));
;             v[1] = gelu_t(v[1] + dd.y * bf2f(uu.x >> 16));
;             v[2] = gelu_t(v[2] + dd.z * bf2f(uu.y & 0xffff));
;             v[3] = gelu_t(v[3] + dd.w * bf2f(uu.y >> 16));
;             *(uint2*)(ys + tok * 512 + ch) = pk4(v);
	v_mfma_f32_16x16x32_bf16 v[44:47], v[32:35], v[100:103], v[44:47]
	v_mfma_f32_16x16x32_bf16 v[48:51], v[32:35], v[108:111], v[48:51]
	v_mfma_f32_16x16x32_bf16 v[0:3], v[32:35], v[116:119], v[0:3]
	v_mfma_f32_16x16x32_bf16 v[32:35], v[84:87], v[80:83], v[56:59]
	v_mfma_f32_16x16x32_bf16 v[56:59], v[84:87], v[100:103], v[76:79]
	v_mfma_f32_16x16x32_bf16 v[68:71], v[84:87], v[108:111], v[68:71]
	v_mfma_f32_16x16x32_bf16 v[8:11], v[84:87], v[116:119], v[8:11]
	v_mfma_f32_16x16x32_bf16 v[64:67], v[104:107], v[80:83], v[64:67]
	v_mfma_f32_16x16x32_bf16 v[4:7], v[112:115], v[80:83], v[4:7]
	ds_read_b128 v[36:39], v88
	ds_read_b128 v[52:55], v92 offset:32768
	ds_read_b128 v[60:63], v88 offset:2048
	ds_read_b128 v[76:79], v92 offset:34816
	ds_read_b128 v[80:83], v88 offset:4096
	ds_read_b128 v[84:87], v92 offset:36864
	ds_read_b128 v[88:91], v88 offset:6144
	ds_read_b128 v[92:95], v92 offset:38912
	v_mfma_f32_16x16x32_bf16 v[72:75], v[104:107], v[100:103], v[72:75]
	v_mfma_f32_16x16x32_bf16 v[24:27], v[104:107], v[108:111], v[24:27]
	v_mfma_f32_16x16x32_bf16 v[16:19], v[104:107], v[116:119], v[16:19]
	v_mfma_f32_16x16x32_bf16 v[12:15], v[112:115], v[100:103], v[12:15]
	v_mfma_f32_16x16x32_bf16 v[20:23], v[112:115], v[108:111], v[20:23]
	v_mfma_f32_16x16x32_bf16 v[28:31], v[112:115], v[116:119], v[28:31]
	s_waitcnt lgkmcnt(6)
	v_mfma_f32_16x16x32_bf16 v[40:43], v[36:39], v[52:55], v[40:43]
	s_waitcnt lgkmcnt(4)
	v_mfma_f32_16x16x32_bf16 v[44:47], v[36:39], v[76:79], v[44:47]
	s_waitcnt lgkmcnt(2)
	v_mfma_f32_16x16x32_bf16 v[48:51], v[36:39], v[84:87], v[48:51]
	s_waitcnt lgkmcnt(0)
	v_mfma_f32_16x16x32_bf16 v[0:3], v[36:39], v[92:95], v[0:3]
	v_mfma_f32_16x16x32_bf16 v[32:35], v[60:63], v[52:55], v[32:35]
	v_mfma_f32_16x16x32_bf16 v[36:39], v[60:63], v[76:79], v[56:59]
	v_mfma_f32_16x16x32_bf16 v[68:71], v[60:63], v[84:87], v[68:71]
	v_mfma_f32_16x16x32_bf16 v[8:11], v[60:63], v[92:95], v[8:11]
	v_mfma_f32_16x16x32_bf16 v[60:63], v[80:83], v[52:55], v[64:67]
	v_mfma_f32_16x16x32_bf16 v[64:67], v[80:83], v[76:79], v[72:75]
	v_mfma_f32_16x16x32_bf16 v[72:75], v[80:83], v[84:87], v[24:27]
	s_nop 2
	v_add_u32_e32 v24, v96, v192
	v_mfma_f32_16x16x32_bf16 v[16:19], v[80:83], v[92:95], v[16:19]
	v_add_u32_e32 v25, v97, v192
	v_mfma_f32_16x16x32_bf16 v[4:7], v[88:91], v[52:55], v[4:7]
	v_mfma_f32_16x16x32_bf16 v[76:79], v[88:91], v[76:79], v[12:15]
	v_mfma_f32_16x16x32_bf16 v[80:83], v[88:91], v[84:87], v[20:23]
	v_mfma_f32_16x16x32_bf16 v[84:87], v[88:91], v[92:95], v[28:31]
	s_nop 0
	ds_read_b128 v[12:15], v24
	ds_read_b128 v[88:91], v25 offset:32768
	ds_read_b128 v[20:23], v24 offset:2048
	ds_read_b128 v[92:95], v25 offset:34816
	ds_read_b128 v[96:99], v24 offset:4096
	ds_read_b128 v[100:103], v25 offset:36864
	ds_read_b128 v[104:107], v24 offset:6144
	ds_read_b128 v[108:111], v25 offset:38912
	s_waitcnt lgkmcnt(0)
	s_barrier
	v_mfma_f32_16x16x32_bf16 v[112:115], v[12:15], v[88:91], v[40:43]
	v_mfma_f32_16x16x32_bf16 v[56:59], v[12:15], v[92:95], v[44:47]
	v_mfma_f32_16x16x32_bf16 v[44:47], v[20:23], v[88:91], v[32:35]
	v_mfma_f32_16x16x32_bf16 v[40:43], v[20:23], v[92:95], v[36:39]
	v_mfma_f32_16x16x32_bf16 v[36:39], v[20:23], v[100:103], v[68:71]
	v_mfma_f32_16x16x32_bf16 v[32:35], v[20:23], v[108:111], v[8:11]
	v_mfma_f32_16x16x32_bf16 v[20:23], v[96:99], v[100:103], v[72:75]
	s_nop 2
	v_or_b32_e32 v75, v199, v193
	v_mfma_f32_16x16x32_bf16 v[8:11], v[104:107], v[92:95], v[76:79]
	v_lshlrev_b32_e32 v134, 11, v75
	v_mov_b32_e32 v73, v135
	v_lshl_add_u64 v[68:69], v[150:151], 0, v[134:135]
	v_or_b32_e32 v78, v198, v188
	v_lshlrev_b32_e32 v72, 1, v78
	v_mfma_f32_16x16x32_bf16 v[28:31], v[96:99], v[88:91], v[60:63]
	v_lshlrev_b32_e32 v134, 1, v144
	v_lshrrev_b32_e32 v74, 4, v78
	v_mfma_f32_16x16x32_bf16 v[24:27], v[96:99], v[92:95], v[64:67]
	v_lshl_add_u64 v[60:61], v[68:69], 0, v[72:73]
	v_lshl_add_u64 v[60:61], v[60:61], 0, v[134:135]
	s_nop 0
	v_lshl_or_b32 v66, v152, 4, v144
	v_ashrrev_i32_e32 v67, 31, v66
	v_lshl_add_u64 v[60:61], v[66:67], 2, s[22:23]
	s_nop 0
	v_mfma_f32_16x16x32_bf16 v[52:55], v[12:15], v[100:103], v[48:51]
	s_waitcnt vmcnt(15)
	v_mov_b64_e32 v[70:71], v[210:211]
	v_lshlrev_b32_e32 v76, 16, v70
	v_and_b32_e32 v77, 0xffff0000, v70
	v_mfma_f32_16x16x32_bf16 v[48:51], v[12:15], v[108:111], v[0:3]
	v_mov_b64_e32 v[62:63], v[242:243]
	v_mov_b64_e32 v[64:65], v[244:245]
	v_pk_fma_f32 v[62:63], v[62:63], v[76:77], v[112:113]
	s_nop 0
	v_mul_f32_e32 v70, 0x3d372713, v62
	v_mul_f32_e32 v70, v62, v70
	v_fma_f32 v70, v62, v70, v62
	v_mul_f32_e32 v70, 0xbfcc422a, v70
	v_mul_f32_e32 v70, 0x3fb8aa3b, v70
	v_exp_f32_e32 v70, v70
	v_mfma_f32_16x16x32_bf16 v[0:3], v[104:107], v[108:111], v[84:87]
	v_add_f32_e32 v70, 1.0, v70
	v_rcp_f32_e32 v76, v70
	v_mul_f32_e32 v70, 0x3d372713, v63
	v_mul_f32_e32 v70, v63, v70
	v_fma_f32 v70, v63, v70, v63
	v_mul_f32_e32 v70, 0xbfcc422a, v70
	v_mul_f32_e32 v70, 0x3fb8aa3b, v70
	v_exp_f32_e32 v70, v70
	v_or_b32_e32 v84, 16, v75
	v_mfma_f32_16x16x32_bf16 v[12:15], v[104:107], v[88:91], v[4:7]
	v_add_f32_e32 v70, 1.0, v70
	v_rcp_f32_e32 v77, v70
	v_lshlrev_b32_e32 v70, 16, v71
	v_and_b32_e32 v71, 0xffff0000, v71
	v_pk_fma_f32 v[64:65], v[64:65], v[70:71], v[114:115]
	v_pk_mul_f32 v[62:63], v[62:63], v[76:77]
	v_mul_f32_e32 v70, 0x3d372713, v64
	v_mul_f32_e32 v71, 0x3d372713, v65
	v_mul_f32_e32 v70, v64, v70
	v_mul_f32_e32 v71, v65, v71
	v_fma_f32 v70, v64, v70, v64
	v_fma_f32 v71, v65, v71, v65
	v_mul_f32_e32 v70, 0xbfcc422a, v70
	v_mul_f32_e32 v71, 0xbfcc422a, v71
	v_mul_f32_e32 v70, 0x3fb8aa3b, v70
	v_mul_f32_e32 v71, 0x3fb8aa3b, v71
	v_exp_f32_e32 v70, v70
	v_exp_f32_e32 v71, v71
	v_cvt_pk_bf16_f32 v76, v62, v63
	v_lshlrev_b32_e32 v62, 16, v75
	v_add_f32_e32 v70, 1.0, v70
	v_add_f32_e32 v71, 1.0, v71
	v_rcp_f32_e32 v70, v70
	v_rcp_f32_e32 v71, v71
	v_mov_b32_e32 v63, v135
	v_mfma_f32_16x16x32_bf16 v[4:7], v[104:107], v[100:103], v[80:83]
	v_mul_f32_e64 v64, v64, v70
	v_mul_f32_e64 v65, v65, v71
	v_cvt_pk_bf16_f32 v77, v64, v65
	v_lshl_add_u64 v[64:65], s[68:69], 0, v[62:63]
	v_lshlrev_b32_e32 v70, 6, v78
	v_mov_b32_e32 v71, v135
	v_lshl_add_u64 v[78:79], v[64:65], 0, v[70:71]
	v_lshlrev_b64 v[62:63], 1, v[66:67]
	v_lshl_add_u64 v[66:67], v[78:79], 0, v[62:63]
	global_store_dwordx2 v[66:67], v[76:77], off
	v_lshlrev_b32_e32 v66, 11, v84
	v_mov_b32_e32 v67, v135
	v_lshl_add_u64 v[66:67], v[150:151], 0, v[66:67]
	v_lshl_add_u64 v[76:77], v[66:67], 0, v[72:73]
	v_lshl_add_u64 v[76:77], v[76:77], 0, v[134:135]
	s_nop 0
	v_mfma_f32_16x16x32_bf16 v[16:19], v[96:99], v[108:111], v[16:19]
	s_nop 0
	s_waitcnt vmcnt(15)
; DI float bf2f(unsigned short h) { return __uint_as_float(((unsigned)h) << 16); }
; DI uint2 pk4(f32x4 v) { return make_uint2(pk2(v[0], v[1]), pk2(v[2], v[3])); }
; DI float gelu_t(float x) { float u = 1.5957691216057308f * (x + 0.044715f * x * x * x); return x * __builtin_amdgcn_rcpf(1.f + __expf(-u)); }
; DI void phase5(const Params& p, unsigned char* smem, const int tid, const int vb, const int nvb) {
;     ...
;         epi_loop(acc, tid, [&](const int epi_f, const int epi_t, const f32x4 accv) __attribute__((always_inline)) {
;             const int m = mt * 128 + epi_f, n = nt * 128 + epi_t;
;             const int t = m >> 4, c = m & 15;
;             const size_t tok = (size_t)n * 64 + t;
;             const int ch = g * 16 + c;
;             uint2 uu = *(const uint2*)(us + (((size_t)g * 512 + n) * 64 + t) * 16 + c);
;             float4 dd = *(const float4*)(dsk + ch);
;             f32x4 v = accv;
;             v[0] = gelu_t(v[0] + dd.x * bf2f(uu.x & 0xffff));
;             v[1] = gelu_t(v[1] + dd.y * bf2f(uu.x >> 16));
;             v[2] = gelu_t(v[2] + dd.z * bf2f(uu.y & 0xffff));
;             v[3] = gelu_t(v[3] + dd.w * bf2f(uu.y >> 16));
;             *(uint2*)(ys + tok * 512 + ch) = pk4(v);
	v_mov_b64_e32 v[80:81], v[212:213]
	v_lshlrev_b32_e32 v82, 16, v80
	v_and_b32_e32 v83, 0xffff0000, v80
	v_mov_b64_e32 v[76:77], v[242:243]
	v_mov_b64_e32 v[78:79], v[244:245]
	v_pk_fma_f32 v[56:57], v[76:77], v[82:83], v[56:57]
	s_nop 0
	v_mul_f32_e32 v76, 0x3d372713, v56
	v_mul_f32_e32 v77, 0x3d372713, v57
	v_mul_f32_e32 v76, v56, v76
	v_mul_f32_e32 v77, v57, v77
	v_fma_f32 v76, v56, v76, v56
	v_fma_f32 v77, v57, v77, v57
	v_mul_f32_e32 v76, 0xbfcc422a, v76
	v_mul_f32_e32 v77, 0xbfcc422a, v77
	v_mul_f32_e32 v76, 0x3fb8aa3b, v76
	v_mul_f32_e32 v77, 0x3fb8aa3b, v77
	v_exp_f32_e32 v76, v76
	v_exp_f32_e32 v77, v77
	v_add_f32_e32 v76, 1.0, v76
	v_add_f32_e32 v77, 1.0, v77
	v_rcp_f32_e32 v76, v76
	v_rcp_f32_e32 v77, v77
	s_nop 0
	v_pk_mul_f32 v[56:57], v[56:57], v[76:77]
	v_lshlrev_b32_e32 v76, 16, v81
	v_and_b32_e32 v77, 0xffff0000, v81
	v_pk_fma_f32 v[58:59], v[78:79], v[76:77], v[58:59]
	s_nop 0
	v_mul_f32_e32 v76, 0x3d372713, v58
	v_mul_f32_e32 v77, 0x3d372713, v59
	v_mul_f32_e32 v76, v58, v76
	v_mul_f32_e32 v77, v59, v77
	v_fma_f32 v76, v58, v76, v58
	v_fma_f32 v77, v59, v77, v59
	v_mul_f32_e32 v76, 0xbfcc422a, v76
	v_mul_f32_e32 v77, 0xbfcc422a, v77
	v_mul_f32_e32 v76, 0x3fb8aa3b, v76
	v_mul_f32_e32 v77, 0x3fb8aa3b, v77
	v_exp_f32_e32 v76, v76
	v_exp_f32_e32 v77, v77
	v_add_f32_e32 v76, 1.0, v76
	v_add_f32_e32 v77, 1.0, v77
	v_rcp_f32_e32 v76, v76
	v_rcp_f32_e32 v77, v77
	s_nop 0
	v_pk_mul_f32 v[58:59], v[58:59], v[76:77]
	v_cvt_pk_bf16_f32 v76, v56, v57
	v_lshlrev_b32_e32 v56, 16, v84
	v_mov_b32_e32 v57, v135
	v_lshl_add_u64 v[56:57], s[68:69], 0, v[56:57]
	v_cvt_pk_bf16_f32 v77, v58, v59
	v_lshl_add_u64 v[58:59], v[56:57], 0, v[70:71]
	v_lshl_add_u64 v[58:59], v[58:59], 0, v[62:63]
	v_or_b32_e32 v84, 32, v75
	global_store_dwordx2 v[58:59], v[76:77], off
	v_lshlrev_b32_e32 v58, 11, v84
	v_mov_b32_e32 v59, v135
	v_lshl_add_u64 v[58:59], v[150:151], 0, v[58:59]
	v_lshl_add_u64 v[76:77], v[58:59], 0, v[72:73]
	v_lshl_add_u64 v[76:77], v[76:77], 0, v[134:135]
	s_nop 0
	v_or_b32_e32 v75, 48, v75
	s_nop 0
	s_waitcnt vmcnt(15)
	v_mov_b64_e32 v[80:81], v[214:215]
	v_lshlrev_b32_e32 v82, 16, v80
	v_and_b32_e32 v83, 0xffff0000, v80
	v_mov_b64_e32 v[76:77], v[242:243]
	v_mov_b64_e32 v[78:79], v[244:245]
	v_pk_fma_f32 v[52:53], v[76:77], v[82:83], v[52:53]
	s_nop 0
	v_mul_f32_e32 v76, 0x3d372713, v52
	v_mul_f32_e32 v77, 0x3d372713, v53
	v_mul_f32_e32 v76, v52, v76
	v_mul_f32_e32 v77, v53, v77
	v_fma_f32 v76, v52, v76, v52
	v_fma_f32 v77, v53, v77, v53
	v_mul_f32_e32 v76, 0xbfcc422a, v76
	v_mul_f32_e32 v77, 0xbfcc422a, v77
	v_mul_f32_e32 v76, 0x3fb8aa3b, v76
	v_mul_f32_e32 v77, 0x3fb8aa3b, v77
	v_exp_f32_e32 v76, v76
	v_exp_f32_e32 v77, v77
	v_add_f32_e32 v76, 1.0, v76
	v_add_f32_e32 v77, 1.0, v77
	v_rcp_f32_e32 v76, v76
	v_rcp_f32_e32 v77, v77
	s_nop 0
	v_pk_mul_f32 v[52:53], v[52:53], v[76:77]
	v_lshlrev_b32_e32 v76, 16, v81
	v_and_b32_e32 v77, 0xffff0000, v81
	v_pk_fma_f32 v[54:55], v[78:79], v[76:77], v[54:55]
	s_nop 0
	v_mul_f32_e32 v76, 0x3d372713, v54
	v_mul_f32_e32 v77, 0x3d372713, v55
	v_mul_f32_e32 v76, v54, v76
	v_mul_f32_e32 v77, v55, v77
	v_fma_f32 v76, v54, v76, v54
	v_fma_f32 v77, v55, v77, v55
	v_mul_f32_e32 v76, 0xbfcc422a, v76
	v_mul_f32_e32 v77, 0xbfcc422a, v77
	v_mul_f32_e32 v76, 0x3fb8aa3b, v76
	v_mul_f32_e32 v77, 0x3fb8aa3b, v77
	v_exp_f32_e32 v76, v76
	v_exp_f32_e32 v77, v77
	v_add_f32_e32 v76, 1.0, v76
	v_add_f32_e32 v77, 1.0, v77
	v_rcp_f32_e32 v76, v76
	v_rcp_f32_e32 v77, v77
	s_nop 0
	v_pk_mul_f32 v[54:55], v[54:55], v[76:77]
	v_cvt_pk_bf16_f32 v76, v52, v53
	v_lshlrev_b32_e32 v52, 16, v84
	v_mov_b32_e32 v53, v135
	v_lshl_add_u64 v[52:53], s[68:69], 0, v[52:53]
	v_cvt_pk_bf16_f32 v77, v54, v55
	v_lshl_add_u64 v[54:55], v[52:53], 0, v[70:71]
	v_lshl_add_u64 v[54:55], v[54:55], 0, v[62:63]
	global_store_dwordx2 v[54:55], v[76:77], off
	v_lshlrev_b32_e32 v54, 11, v75
	v_mov_b32_e32 v55, v135
	v_lshl_add_u64 v[54:55], v[150:151], 0, v[54:55]
	v_lshl_add_u64 v[72:73], v[54:55], 0, v[72:73]
	v_lshl_add_u64 v[72:73], v[72:73], 0, v[134:135]
	s_waitcnt vmcnt(15)
	v_mov_b64_e32 v[72:73], v[216:217]
	v_lshlrev_b32_e32 v80, 16, v72
	v_and_b32_e32 v81, 0xffff0000, v72
	v_mov_b64_e32 v[76:77], v[242:243]
	v_mov_b64_e32 v[78:79], v[244:245]
	v_pk_fma_f32 v[48:49], v[76:77], v[80:81], v[48:49]
	s_nop 0
	v_mul_f32_e32 v72, 0x3d372713, v48
	v_mul_f32_e32 v72, v48, v72
	v_fma_f32 v72, v48, v72, v48
	v_mul_f32_e32 v72, 0xbfcc422a, v72
	v_mul_f32_e32 v72, 0x3fb8aa3b, v72
	v_exp_f32_e32 v72, v72
	s_nop 0
	v_add_f32_e32 v72, 1.0, v72
	v_rcp_f32_e32 v76, v72
	v_mul_f32_e32 v72, 0x3d372713, v49
	v_mul_f32_e32 v72, v49, v72
	v_fma_f32 v72, v49, v72, v49
	v_mul_f32_e32 v72, 0xbfcc422a, v72
	v_mul_f32_e32 v72, 0x3fb8aa3b, v72
	v_exp_f32_e32 v72, v72
	s_nop 0
	v_add_f32_e32 v72, 1.0, v72
	v_rcp_f32_e32 v77, v72
	v_lshlrev_b32_e32 v72, 16, v73
	v_and_b32_e32 v73, 0xffff0000, v73
	v_pk_fma_f32 v[50:51], v[78:79], v[72:73], v[50:51]
	v_pk_mul_f32 v[48:49], v[48:49], v[76:77]
	v_mul_f32_e32 v72, 0x3d372713, v50
	v_mul_f32_e32 v73, 0x3d372713, v51
	v_mul_f32_e32 v72, v50, v72
	v_mul_f32_e32 v73, v51, v73
	v_fma_f32 v72, v50, v72, v50
	v_fma_f32 v73, v51, v73, v51
	v_mul_f32_e32 v72, 0xbfcc422a, v72
	v_mul_f32_e32 v73, 0xbfcc422a, v73
	v_mul_f32_e32 v72, 0x3fb8aa3b, v72
	v_mul_f32_e32 v73, 0x3fb8aa3b, v73
	v_exp_f32_e32 v72, v72
	v_exp_f32_e32 v73, v73
	v_add_f32_e32 v72, 1.0, v72
	v_add_f32_e32 v73, 1.0, v73
	v_rcp_f32_e32 v72, v72
	v_rcp_f32_e32 v73, v73
	s_nop 0
	v_pk_mul_f32 v[50:51], v[50:51], v[72:73]
	v_cvt_pk_bf16_f32 v72, v48, v49
	v_lshlrev_b32_e32 v48, 16, v75
	v_mov_b32_e32 v49, v135
	v_lshl_add_u64 v[48:49], s[68:69], 0, v[48:49]
	v_cvt_pk_bf16_f32 v73, v50, v51
	v_lshl_add_u64 v[50:51], v[48:49], 0, v[70:71]
	v_lshl_add_u64 v[50:51], v[50:51], 0, v[62:63]
	v_or_b32_e32 v75, 1, v74
	global_store_dwordx2 v[50:51], v[72:73], off
	v_lshlrev_b32_e32 v50, 5, v75
	v_mov_b32_e32 v51, v135
	v_lshl_add_u64 v[70:71], v[68:69], 0, v[50:51]
	v_lshl_add_u64 v[70:71], v[70:71], 0, v[134:135]
	s_waitcnt vmcnt(15)
; DI float bf2f(unsigned short h) { return __uint_as_float(((unsigned)h) << 16); }
; DI uint2 pk4(f32x4 v) { return make_uint2(pk2(v[0], v[1]), pk2(v[2], v[3])); }
; DI float gelu_t(float x) { float u = 1.5957691216057308f * (x + 0.044715f * x * x * x); return x * __builtin_amdgcn_rcpf(1.f + __expf(-u)); }
; DI void phase5(const Params& p, unsigned char* smem, const int tid, const int vb, const int nvb) {
;     ...
;         epi_loop(acc, tid, [&](const int epi_f, const int epi_t, const f32x4 accv) __attribute__((always_inline)) {
;             const int m = mt * 128 + epi_f, n = nt * 128 + epi_t;
;             const int t = m >> 4, c = m & 15;
;             const size_t tok = (size_t)n * 64 + t;
;             const int ch = g * 16 + c;
;             uint2 uu = *(const uint2*)(us + (((size_t)g * 512 + n) * 64 + t) * 16 + c);
;             float4 dd = *(const float4*)(dsk + ch);
;             f32x4 v = accv;
;             v[0] = gelu_t(v[0] + dd.x * bf2f(uu.x & 0xffff));
;             v[1] = gelu_t(v[1] + dd.y * bf2f(uu.x >> 16));
;             v[2] = gelu_t(v[2] + dd.z * bf2f(uu.y & 0xffff));
;             v[3] = gelu_t(v[3] + dd.w * bf2f(uu.y >> 16));
;             *(uint2*)(ys + tok * 512 + ch) = pk4(v);
	v_mov_b64_e32 v[76:77], v[218:219]
	v_lshlrev_b32_e32 v78, 16, v76
	v_and_b32_e32 v79, 0xffff0000, v76
	v_mov_b64_e32 v[70:71], v[242:243]
	v_mov_b64_e32 v[72:73], v[244:245]
	v_pk_fma_f32 v[44:45], v[70:71], v[78:79], v[44:45]
	s_nop 0
	v_mul_f32_e32 v70, 0x3d372713, v44
	v_mul_f32_e32 v71, 0x3d372713, v45
	v_mul_f32_e32 v70, v44, v70
	v_mul_f32_e32 v71, v45, v71
	v_fma_f32 v70, v44, v70, v44
	v_fma_f32 v71, v45, v71, v45
	v_mul_f32_e32 v70, 0xbfcc422a, v70
	v_mul_f32_e32 v71, 0xbfcc422a, v71
	v_mul_f32_e32 v70, 0x3fb8aa3b, v70
	v_mul_f32_e32 v71, 0x3fb8aa3b, v71
	v_exp_f32_e32 v70, v70
	v_exp_f32_e32 v71, v71
	v_add_f32_e32 v70, 1.0, v70
	v_add_f32_e32 v71, 1.0, v71
	v_rcp_f32_e32 v70, v70
	v_rcp_f32_e32 v71, v71
	s_nop 0
	v_pk_mul_f32 v[44:45], v[44:45], v[70:71]
	v_lshlrev_b32_e32 v70, 16, v77
	v_and_b32_e32 v71, 0xffff0000, v77
	v_pk_fma_f32 v[46:47], v[72:73], v[70:71], v[46:47]
	s_nop 0
	v_mul_f32_e32 v70, 0x3d372713, v46
	v_mul_f32_e32 v71, 0x3d372713, v47
	v_mul_f32_e32 v70, v46, v70
	v_mul_f32_e32 v71, v47, v71
	v_fma_f32 v70, v46, v70, v46
	v_fma_f32 v71, v47, v71, v47
	v_mul_f32_e32 v70, 0xbfcc422a, v70
	v_mul_f32_e32 v71, 0xbfcc422a, v71
	v_mul_f32_e32 v70, 0x3fb8aa3b, v70
	v_mul_f32_e32 v71, 0x3fb8aa3b, v71
	v_exp_f32_e32 v70, v70
	v_exp_f32_e32 v71, v71
	v_add_f32_e32 v70, 1.0, v70
	v_add_f32_e32 v71, 1.0, v71
	v_rcp_f32_e32 v70, v70
	v_rcp_f32_e32 v71, v71
	s_nop 0
	v_pk_mul_f32 v[46:47], v[46:47], v[70:71]
	v_cvt_pk_bf16_f32 v70, v44, v45
	v_lshlrev_b32_e32 v44, 10, v75
	v_mov_b32_e32 v45, v135
	v_cvt_pk_bf16_f32 v71, v46, v47
	v_lshl_add_u64 v[46:47], v[64:65], 0, v[44:45]
	v_lshl_add_u64 v[46:47], v[46:47], 0, v[62:63]
	global_store_dwordx2 v[46:47], v[70:71], off
	v_lshl_add_u64 v[46:47], v[66:67], 0, v[50:51]
	v_lshl_add_u64 v[46:47], v[46:47], 0, v[134:135]
	s_waitcnt vmcnt(15)
	v_mov_b64_e32 v[46:47], v[220:221]
	v_lshlrev_b32_e32 v76, 16, v46
	v_and_b32_e32 v77, 0xffff0000, v46
	v_mov_b64_e32 v[70:71], v[242:243]
	v_mov_b64_e32 v[72:73], v[244:245]
	v_pk_fma_f32 v[40:41], v[70:71], v[76:77], v[40:41]
	s_nop 0
	v_mul_f32_e32 v46, 0x3d372713, v40
	v_mul_f32_e32 v46, v40, v46
	v_fma_f32 v46, v40, v46, v40
	v_mul_f32_e32 v46, 0xbfcc422a, v46
	v_mul_f32_e32 v46, 0x3fb8aa3b, v46
	v_exp_f32_e32 v46, v46
	s_nop 0
	v_add_f32_e32 v46, 1.0, v46
	v_rcp_f32_e32 v70, v46
	v_mul_f32_e32 v46, 0x3d372713, v41
	v_mul_f32_e32 v46, v41, v46
	v_fma_f32 v46, v41, v46, v41
	v_mul_f32_e32 v46, 0xbfcc422a, v46
	v_mul_f32_e32 v46, 0x3fb8aa3b, v46
	v_exp_f32_e32 v46, v46
	s_nop 0
	v_add_f32_e32 v46, 1.0, v46
	v_rcp_f32_e32 v71, v46
	v_lshlrev_b32_e32 v46, 16, v47
	v_and_b32_e32 v47, 0xffff0000, v47
	v_pk_fma_f32 v[42:43], v[72:73], v[46:47], v[42:43]
	v_pk_mul_f32 v[40:41], v[40:41], v[70:71]
	v_mul_f32_e32 v46, 0x3d372713, v42
	v_mul_f32_e32 v47, 0x3d372713, v43
	v_mul_f32_e32 v46, v42, v46
	v_mul_f32_e32 v47, v43, v47
	v_fma_f32 v46, v42, v46, v42
	v_fma_f32 v47, v43, v47, v43
	v_mul_f32_e32 v46, 0xbfcc422a, v46
	v_mul_f32_e32 v47, 0xbfcc422a, v47
	v_mul_f32_e32 v46, 0x3fb8aa3b, v46
	v_mul_f32_e32 v47, 0x3fb8aa3b, v47
	v_exp_f32_e32 v46, v46
	v_exp_f32_e32 v47, v47
	v_cvt_pk_bf16_f32 v40, v40, v41
	v_add_f32_e32 v46, 1.0, v46
	v_add_f32_e32 v47, 1.0, v47
	v_rcp_f32_e32 v46, v46
	v_rcp_f32_e32 v47, v47
	s_nop 0
	v_pk_mul_f32 v[42:43], v[42:43], v[46:47]
	s_nop 0
	v_cvt_pk_bf16_f32 v41, v42, v43
	v_lshl_add_u64 v[42:43], v[56:57], 0, v[44:45]
	v_lshl_add_u64 v[42:43], v[42:43], 0, v[62:63]
	global_store_dwordx2 v[42:43], v[40:41], off
	v_lshl_add_u64 v[40:41], v[58:59], 0, v[50:51]
	v_lshl_add_u64 v[40:41], v[40:41], 0, v[134:135]
	s_waitcnt vmcnt(15)
	v_mov_b64_e32 v[46:47], v[222:223]
	v_lshlrev_b32_e32 v70, 16, v46
	v_and_b32_e32 v71, 0xffff0000, v46
	v_mov_b64_e32 v[40:41], v[242:243]
	v_mov_b64_e32 v[42:43], v[244:245]
	v_pk_fma_f32 v[36:37], v[40:41], v[70:71], v[36:37]
	s_nop 0
	v_mul_f32_e32 v40, 0x3d372713, v36
	v_mul_f32_e32 v41, 0x3d372713, v37
	v_mul_f32_e32 v40, v36, v40
	v_mul_f32_e32 v41, v37, v41
	v_fma_f32 v40, v36, v40, v36
	v_fma_f32 v41, v37, v41, v37
	v_mul_f32_e32 v40, 0xbfcc422a, v40
	v_mul_f32_e32 v41, 0xbfcc422a, v41
	v_mul_f32_e32 v40, 0x3fb8aa3b, v40
	v_mul_f32_e32 v41, 0x3fb8aa3b, v41
	v_exp_f32_e32 v40, v40
	v_exp_f32_e32 v41, v41
	v_add_f32_e32 v40, 1.0, v40
	v_add_f32_e32 v41, 1.0, v41
	v_rcp_f32_e32 v40, v40
	v_rcp_f32_e32 v41, v41
	s_nop 0
	v_pk_mul_f32 v[36:37], v[36:37], v[40:41]
	v_lshlrev_b32_e32 v40, 16, v47
	v_and_b32_e32 v41, 0xffff0000, v47
	v_pk_fma_f32 v[38:39], v[42:43], v[40:41], v[38:39]
	v_cvt_pk_bf16_f32 v36, v36, v37
	v_mul_f32_e32 v40, 0x3d372713, v38
	v_mul_f32_e32 v41, 0x3d372713, v39
	v_mul_f32_e32 v40, v38, v40
	v_mul_f32_e32 v41, v39, v41
	v_fma_f32 v40, v38, v40, v38
	v_fma_f32 v41, v39, v41, v39
	v_mul_f32_e32 v40, 0xbfcc422a, v40
	v_mul_f32_e32 v41, 0xbfcc422a, v41
	v_mul_f32_e32 v40, 0x3fb8aa3b, v40
	v_mul_f32_e32 v41, 0x3fb8aa3b, v41
	v_exp_f32_e32 v40, v40
	v_exp_f32_e32 v41, v41
	v_add_f32_e32 v40, 1.0, v40
	v_add_f32_e32 v41, 1.0, v41
	v_rcp_f32_e32 v40, v40
	v_rcp_f32_e32 v41, v41
	s_nop 0
	v_pk_mul_f32 v[38:39], v[38:39], v[40:41]
	s_nop 0
	v_cvt_pk_bf16_f32 v37, v38, v39
	v_lshl_add_u64 v[38:39], v[52:53], 0, v[44:45]
	v_lshl_add_u64 v[38:39], v[38:39], 0, v[62:63]
	global_store_dwordx2 v[38:39], v[36:37], off
	v_lshl_add_u64 v[36:37], v[54:55], 0, v[50:51]
	v_lshl_add_u64 v[36:37], v[36:37], 0, v[134:135]
	s_waitcnt vmcnt(15)
; DI float bf2f(unsigned short h) { return __uint_as_float(((unsigned)h) << 16); }
; DI uint2 pk4(f32x4 v) { return make_uint2(pk2(v[0], v[1]), pk2(v[2], v[3])); }
; DI float gelu_t(float x) { float u = 1.5957691216057308f * (x + 0.044715f * x * x * x); return x * __builtin_amdgcn_rcpf(1.f + __expf(-u)); }
; DI void phase5(const Params& p, unsigned char* smem, const int tid, const int vb, const int nvb) {
;     ...
;         epi_loop(acc, tid, [&](const int epi_f, const int epi_t, const f32x4 accv) __attribute__((always_inline)) {
;             const int m = mt * 128 + epi_f, n = nt * 128 + epi_t;
;             const int t = m >> 4, c = m & 15;
;             const size_t tok = (size_t)n * 64 + t;
;             const int ch = g * 16 + c;
;             uint2 uu = *(const uint2*)(us + (((size_t)g * 512 + n) * 64 + t) * 16 + c);
;             float4 dd = *(const float4*)(dsk + ch);
;             f32x4 v = accv;
;             v[0] = gelu_t(v[0] + dd.x * bf2f(uu.x & 0xffff));
;             v[1] = gelu_t(v[1] + dd.y * bf2f(uu.x >> 16));
;             v[2] = gelu_t(v[2] + dd.z * bf2f(uu.y & 0xffff));
;             v[3] = gelu_t(v[3] + dd.w * bf2f(uu.y >> 16));
;             *(uint2*)(ys + tok * 512 + ch) = pk4(v);
	v_mov_b64_e32 v[40:41], v[224:225]
	v_lshlrev_b32_e32 v42, 16, v40
	v_and_b32_e32 v43, 0xffff0000, v40
	v_mov_b64_e32 v[36:37], v[242:243]
	v_mov_b64_e32 v[38:39], v[244:245]
	v_pk_fma_f32 v[32:33], v[36:37], v[42:43], v[32:33]
	s_nop 0
	v_mul_f32_e32 v36, 0x3d372713, v32
	v_mul_f32_e32 v37, 0x3d372713, v33
	v_mul_f32_e32 v36, v32, v36
	v_mul_f32_e32 v37, v33, v37
	v_fma_f32 v36, v32, v36, v32
	v_fma_f32 v37, v33, v37, v33
	v_mul_f32_e32 v36, 0xbfcc422a, v36
	v_mul_f32_e32 v37, 0xbfcc422a, v37
	v_mul_f32_e32 v36, 0x3fb8aa3b, v36
	v_mul_f32_e32 v37, 0x3fb8aa3b, v37
	v_exp_f32_e32 v36, v36
	v_exp_f32_e32 v37, v37
	v_or_b32_e32 v42, 2, v74
	v_add_f32_e32 v36, 1.0, v36
	v_add_f32_e32 v37, 1.0, v37
	v_rcp_f32_e32 v36, v36
	v_rcp_f32_e32 v37, v37
	s_nop 0
	v_pk_mul_f32 v[32:33], v[32:33], v[36:37]
	v_lshlrev_b32_e32 v36, 16, v41
	v_and_b32_e32 v37, 0xffff0000, v41
	v_pk_fma_f32 v[34:35], v[38:39], v[36:37], v[34:35]
	v_cvt_pk_bf16_f32 v32, v32, v33
	v_mul_f32_e32 v36, 0x3d372713, v34
	v_mul_f32_e32 v37, 0x3d372713, v35
	v_mul_f32_e32 v36, v34, v36
	v_mul_f32_e32 v37, v35, v37
	v_fma_f32 v36, v34, v36, v34
	v_fma_f32 v37, v35, v37, v35
	v_mul_f32_e32 v36, 0xbfcc422a, v36
	v_mul_f32_e32 v37, 0xbfcc422a, v37
	v_mul_f32_e32 v36, 0x3fb8aa3b, v36
	v_mul_f32_e32 v37, 0x3fb8aa3b, v37
	v_exp_f32_e32 v36, v36
	v_exp_f32_e32 v37, v37
	v_add_f32_e32 v36, 1.0, v36
	v_add_f32_e32 v37, 1.0, v37
	v_rcp_f32_e32 v36, v36
	v_rcp_f32_e32 v37, v37
	s_nop 0
	v_pk_mul_f32 v[34:35], v[34:35], v[36:37]
	s_nop 0
	v_cvt_pk_bf16_f32 v33, v34, v35
	v_lshl_add_u64 v[34:35], v[48:49], 0, v[44:45]
	v_lshl_add_u64 v[34:35], v[34:35], 0, v[62:63]
	global_store_dwordx2 v[34:35], v[32:33], off
	v_lshlrev_b32_e32 v32, 5, v42
	v_mov_b32_e32 v33, v135
	v_lshl_add_u64 v[34:35], v[68:69], 0, v[32:33]
	v_lshl_add_u64 v[34:35], v[34:35], 0, v[134:135]
	s_waitcnt vmcnt(15)
	v_mov_b64_e32 v[38:39], v[226:227]
	v_lshlrev_b32_e32 v40, 16, v38
	v_and_b32_e32 v41, 0xffff0000, v38
	v_mov_b64_e32 v[34:35], v[242:243]
	v_mov_b64_e32 v[36:37], v[244:245]
	v_pk_fma_f32 v[28:29], v[34:35], v[40:41], v[28:29]
	s_nop 0
	v_mul_f32_e32 v34, 0x3d372713, v28
	v_mul_f32_e32 v35, 0x3d372713, v29
	v_mul_f32_e32 v34, v28, v34
	v_mul_f32_e32 v35, v29, v35
	v_fma_f32 v34, v28, v34, v28
	v_fma_f32 v35, v29, v35, v29
	v_mul_f32_e32 v34, 0xbfcc422a, v34
	v_mul_f32_e32 v35, 0xbfcc422a, v35
	v_mul_f32_e32 v34, 0x3fb8aa3b, v34
	v_mul_f32_e32 v35, 0x3fb8aa3b, v35
	v_exp_f32_e32 v34, v34
	v_exp_f32_e32 v35, v35
	v_add_f32_e32 v34, 1.0, v34
	v_add_f32_e32 v35, 1.0, v35
	v_rcp_f32_e32 v34, v34
	v_rcp_f32_e32 v35, v35
	s_nop 0
	v_pk_mul_f32 v[28:29], v[28:29], v[34:35]
	v_lshlrev_b32_e32 v34, 16, v39
	v_and_b32_e32 v35, 0xffff0000, v39
	v_pk_fma_f32 v[30:31], v[36:37], v[34:35], v[30:31]
	s_nop 0
	v_mul_f32_e32 v34, 0x3d372713, v30
	v_mul_f32_e32 v35, 0x3d372713, v31
	v_mul_f32_e32 v34, v30, v34
	v_mul_f32_e32 v35, v31, v35
	v_fma_f32 v34, v30, v34, v30
	v_fma_f32 v35, v31, v35, v31
	v_mul_f32_e32 v34, 0xbfcc422a, v34
	v_mul_f32_e32 v35, 0xbfcc422a, v35
	v_mul_f32_e32 v34, 0x3fb8aa3b, v34
	v_mul_f32_e32 v35, 0x3fb8aa3b, v35
	v_exp_f32_e32 v34, v34
	v_exp_f32_e32 v35, v35
	v_add_f32_e32 v34, 1.0, v34
	v_add_f32_e32 v35, 1.0, v35
	v_rcp_f32_e32 v34, v34
	v_rcp_f32_e32 v35, v35
	s_nop 0
	v_pk_mul_f32 v[30:31], v[30:31], v[34:35]
	v_cvt_pk_bf16_f32 v34, v28, v29
	v_lshlrev_b32_e32 v28, 10, v42
	v_mov_b32_e32 v29, v135
	v_cvt_pk_bf16_f32 v35, v30, v31
	v_lshl_add_u64 v[30:31], v[64:65], 0, v[28:29]
	v_lshl_add_u64 v[30:31], v[30:31], 0, v[62:63]
	global_store_dwordx2 v[30:31], v[34:35], off
	v_lshl_add_u64 v[30:31], v[66:67], 0, v[32:33]
	v_lshl_add_u64 v[30:31], v[30:31], 0, v[134:135]
	s_waitcnt vmcnt(15)
	v_mov_b64_e32 v[30:31], v[228:229]
	v_lshlrev_b32_e32 v38, 16, v30
	v_and_b32_e32 v39, 0xffff0000, v30
	v_mov_b64_e32 v[34:35], v[242:243]
	v_mov_b64_e32 v[36:37], v[244:245]
	v_pk_fma_f32 v[24:25], v[34:35], v[38:39], v[24:25]
	s_nop 0
	v_mul_f32_e32 v30, 0x3d372713, v24
	v_mul_f32_e32 v30, v24, v30
	v_fma_f32 v30, v24, v30, v24
	v_mul_f32_e32 v30, 0xbfcc422a, v30
	v_mul_f32_e32 v30, 0x3fb8aa3b, v30
	v_exp_f32_e32 v30, v30
	s_nop 0
	v_add_f32_e32 v30, 1.0, v30
	v_rcp_f32_e32 v34, v30
	v_mul_f32_e32 v30, 0x3d372713, v25
	v_mul_f32_e32 v30, v25, v30
	v_fma_f32 v30, v25, v30, v25
	v_mul_f32_e32 v30, 0xbfcc422a, v30
	v_mul_f32_e32 v30, 0x3fb8aa3b, v30
	v_exp_f32_e32 v30, v30
	s_nop 0
	v_add_f32_e32 v30, 1.0, v30
	v_rcp_f32_e32 v35, v30
	v_lshlrev_b32_e32 v30, 16, v31
	v_and_b32_e32 v31, 0xffff0000, v31
	v_pk_fma_f32 v[26:27], v[36:37], v[30:31], v[26:27]
	v_pk_mul_f32 v[24:25], v[24:25], v[34:35]
	v_mul_f32_e32 v30, 0x3d372713, v26
	v_mul_f32_e32 v31, 0x3d372713, v27
	v_mul_f32_e32 v30, v26, v30
	v_mul_f32_e32 v31, v27, v31
	v_fma_f32 v30, v26, v30, v26
	v_fma_f32 v31, v27, v31, v27
	v_mul_f32_e32 v30, 0xbfcc422a, v30
	v_mul_f32_e32 v31, 0xbfcc422a, v31
	v_mul_f32_e32 v30, 0x3fb8aa3b, v30
	v_mul_f32_e32 v31, 0x3fb8aa3b, v31
	v_exp_f32_e32 v30, v30
	v_exp_f32_e32 v31, v31
	v_cvt_pk_bf16_f32 v24, v24, v25
	v_add_f32_e32 v30, 1.0, v30
	v_add_f32_e32 v31, 1.0, v31
	v_rcp_f32_e32 v30, v30
	v_rcp_f32_e32 v31, v31
	s_nop 0
	v_pk_mul_f32 v[26:27], v[26:27], v[30:31]
	s_nop 0
	v_cvt_pk_bf16_f32 v25, v26, v27
	v_lshl_add_u64 v[26:27], v[56:57], 0, v[28:29]
	v_lshl_add_u64 v[26:27], v[26:27], 0, v[62:63]
	global_store_dwordx2 v[26:27], v[24:25], off
	v_lshl_add_u64 v[24:25], v[58:59], 0, v[32:33]
	v_lshl_add_u64 v[24:25], v[24:25], 0, v[134:135]
	s_waitcnt vmcnt(15)
; DI float bf2f(unsigned short h) { return __uint_as_float(((unsigned)h) << 16); }
; DI uint2 pk4(f32x4 v) { return make_uint2(pk2(v[0], v[1]), pk2(v[2], v[3])); }
; DI float gelu_t(float x) { float u = 1.5957691216057308f * (x + 0.044715f * x * x * x); return x * __builtin_amdgcn_rcpf(1.f + __expf(-u)); }
; DI void phase5(const Params& p, unsigned char* smem, const int tid, const int vb, const int nvb) {
;     ...
;         epi_loop(acc, tid, [&](const int epi_f, const int epi_t, const f32x4 accv) __attribute__((always_inline)) {
;             const int m = mt * 128 + epi_f, n = nt * 128 + epi_t;
;             const int t = m >> 4, c = m & 15;
;             const size_t tok = (size_t)n * 64 + t;
;             const int ch = g * 16 + c;
;             uint2 uu = *(const uint2*)(us + (((size_t)g * 512 + n) * 64 + t) * 16 + c);
;             float4 dd = *(const float4*)(dsk + ch);
;             f32x4 v = accv;
;             v[0] = gelu_t(v[0] + dd.x * bf2f(uu.x & 0xffff));
;             v[1] = gelu_t(v[1] + dd.y * bf2f(uu.x >> 16));
;             v[2] = gelu_t(v[2] + dd.z * bf2f(uu.y & 0xffff));
;             v[3] = gelu_t(v[3] + dd.w * bf2f(uu.y >> 16));
;             *(uint2*)(ys + tok * 512 + ch) = pk4(v);
	v_mov_b64_e32 v[30:31], v[230:231]
	v_lshlrev_b32_e32 v34, 16, v30
	v_and_b32_e32 v35, 0xffff0000, v30
	v_mov_b64_e32 v[24:25], v[242:243]
	v_mov_b64_e32 v[26:27], v[244:245]
	v_pk_fma_f32 v[20:21], v[24:25], v[34:35], v[20:21]
	s_nop 0
	v_mul_f32_e32 v24, 0x3d372713, v20
	v_mul_f32_e32 v25, 0x3d372713, v21
	v_mul_f32_e32 v24, v20, v24
	v_mul_f32_e32 v25, v21, v25
	v_fma_f32 v24, v20, v24, v20
	v_fma_f32 v25, v21, v25, v21
	v_mul_f32_e32 v24, 0xbfcc422a, v24
	v_mul_f32_e32 v25, 0xbfcc422a, v25
	v_mul_f32_e32 v24, 0x3fb8aa3b, v24
	v_mul_f32_e32 v25, 0x3fb8aa3b, v25
	v_exp_f32_e32 v24, v24
	v_exp_f32_e32 v25, v25
	v_add_f32_e32 v24, 1.0, v24
	v_add_f32_e32 v25, 1.0, v25
	v_rcp_f32_e32 v24, v24
	v_rcp_f32_e32 v25, v25
	s_nop 0
	v_pk_mul_f32 v[20:21], v[20:21], v[24:25]
	v_lshlrev_b32_e32 v24, 16, v31
	v_and_b32_e32 v25, 0xffff0000, v31
	v_pk_fma_f32 v[22:23], v[26:27], v[24:25], v[22:23]
	v_cvt_pk_bf16_f32 v20, v20, v21
	v_mul_f32_e32 v24, 0x3d372713, v22
	v_mul_f32_e32 v25, 0x3d372713, v23
	v_mul_f32_e32 v24, v22, v24
	v_mul_f32_e32 v25, v23, v25
	v_fma_f32 v24, v22, v24, v22
	v_fma_f32 v25, v23, v25, v23
	v_mul_f32_e32 v24, 0xbfcc422a, v24
	v_mul_f32_e32 v25, 0xbfcc422a, v25
	v_mul_f32_e32 v24, 0x3fb8aa3b, v24
	v_mul_f32_e32 v25, 0x3fb8aa3b, v25
	v_exp_f32_e32 v24, v24
	v_exp_f32_e32 v25, v25
	v_add_f32_e32 v24, 1.0, v24
	v_add_f32_e32 v25, 1.0, v25
	v_rcp_f32_e32 v24, v24
	v_rcp_f32_e32 v25, v25
	s_nop 0
	v_pk_mul_f32 v[22:23], v[22:23], v[24:25]
	s_nop 0
	v_cvt_pk_bf16_f32 v21, v22, v23
	v_lshl_add_u64 v[22:23], v[52:53], 0, v[28:29]
	v_lshl_add_u64 v[22:23], v[22:23], 0, v[62:63]
	global_store_dwordx2 v[22:23], v[20:21], off
	v_lshl_add_u64 v[20:21], v[54:55], 0, v[32:33]
	v_lshl_add_u64 v[20:21], v[20:21], 0, v[134:135]
	s_waitcnt vmcnt(15)
	v_mov_b64_e32 v[24:25], v[232:233]
	v_lshlrev_b32_e32 v26, 16, v24
	v_and_b32_e32 v27, 0xffff0000, v24
	v_mov_b64_e32 v[20:21], v[242:243]
	v_mov_b64_e32 v[22:23], v[244:245]
	v_pk_fma_f32 v[16:17], v[20:21], v[26:27], v[16:17]
	s_nop 0
	v_mul_f32_e32 v20, 0x3d372713, v16
	v_mul_f32_e32 v21, 0x3d372713, v17
	v_mul_f32_e32 v20, v16, v20
	v_mul_f32_e32 v21, v17, v21
	v_fma_f32 v20, v16, v20, v16
	v_fma_f32 v21, v17, v21, v17
	v_mul_f32_e32 v20, 0xbfcc422a, v20
	v_mul_f32_e32 v21, 0xbfcc422a, v21
	v_mul_f32_e32 v20, 0x3fb8aa3b, v20
	v_mul_f32_e32 v21, 0x3fb8aa3b, v21
	v_exp_f32_e32 v20, v20
	v_exp_f32_e32 v21, v21
	v_add_f32_e32 v20, 1.0, v20
	v_add_f32_e32 v21, 1.0, v21
	v_rcp_f32_e32 v20, v20
	v_rcp_f32_e32 v21, v21
	s_nop 0
	v_pk_mul_f32 v[16:17], v[16:17], v[20:21]
	v_lshlrev_b32_e32 v20, 16, v25
	v_and_b32_e32 v21, 0xffff0000, v25
	v_pk_fma_f32 v[18:19], v[22:23], v[20:21], v[18:19]
	v_cvt_pk_bf16_f32 v16, v16, v17
	v_mul_f32_e32 v20, 0x3d372713, v18
	v_mul_f32_e32 v21, 0x3d372713, v19
	v_mul_f32_e32 v20, v18, v20
	v_mul_f32_e32 v21, v19, v21
	v_fma_f32 v20, v18, v20, v18
	v_fma_f32 v21, v19, v21, v19
	v_mul_f32_e32 v20, 0xbfcc422a, v20
	v_mul_f32_e32 v21, 0xbfcc422a, v21
	v_mul_f32_e32 v20, 0x3fb8aa3b, v20
	v_mul_f32_e32 v21, 0x3fb8aa3b, v21
	v_exp_f32_e32 v20, v20
	v_exp_f32_e32 v21, v21
	v_add_f32_e32 v20, 1.0, v20
	v_add_f32_e32 v21, 1.0, v21
	v_rcp_f32_e32 v20, v20
	v_rcp_f32_e32 v21, v21
	s_nop 0
	v_pk_mul_f32 v[18:19], v[18:19], v[20:21]
	s_nop 0
	v_cvt_pk_bf16_f32 v17, v18, v19
	v_lshl_add_u64 v[18:19], v[48:49], 0, v[28:29]
	v_lshl_add_u64 v[18:19], v[18:19], 0, v[62:63]
	global_store_dwordx2 v[18:19], v[16:17], off
	v_or_b32_e32 v16, v198, v140
	v_lshrrev_b32_e32 v16, 4, v16
	v_or_b32_e32 v26, 3, v16
	v_lshlrev_b32_e32 v16, 5, v26
	v_mov_b32_e32 v17, v135
	v_lshl_add_u64 v[18:19], v[68:69], 0, v[16:17]
	v_lshl_add_u64 v[18:19], v[18:19], 0, v[134:135]
	s_waitcnt vmcnt(15)
	v_mov_b64_e32 v[22:23], v[234:235]
	v_lshlrev_b32_e32 v24, 16, v22
	v_and_b32_e32 v25, 0xffff0000, v22
	v_mov_b64_e32 v[18:19], v[242:243]
	v_mov_b64_e32 v[20:21], v[244:245]
	v_pk_fma_f32 v[12:13], v[18:19], v[24:25], v[12:13]
	s_nop 0
	v_mul_f32_e32 v18, 0x3d372713, v12
	v_mul_f32_e32 v19, 0x3d372713, v13
	v_mul_f32_e32 v18, v12, v18
	v_mul_f32_e32 v19, v13, v19
	v_fma_f32 v18, v12, v18, v12
	v_fma_f32 v19, v13, v19, v13
	v_mul_f32_e32 v18, 0xbfcc422a, v18
	v_mul_f32_e32 v19, 0xbfcc422a, v19
	v_mul_f32_e32 v18, 0x3fb8aa3b, v18
	v_mul_f32_e32 v19, 0x3fb8aa3b, v19
	v_exp_f32_e32 v18, v18
	v_exp_f32_e32 v19, v19
	v_add_f32_e32 v18, 1.0, v18
	v_add_f32_e32 v19, 1.0, v19
	v_rcp_f32_e32 v18, v18
	v_rcp_f32_e32 v19, v19
	s_nop 0
	v_pk_mul_f32 v[12:13], v[12:13], v[18:19]
	v_lshlrev_b32_e32 v18, 16, v23
	v_and_b32_e32 v19, 0xffff0000, v23
	v_pk_fma_f32 v[14:15], v[20:21], v[18:19], v[14:15]
	s_nop 0
	v_mul_f32_e32 v18, 0x3d372713, v14
	v_mul_f32_e32 v19, 0x3d372713, v15
	v_mul_f32_e32 v18, v14, v18
	v_mul_f32_e32 v19, v15, v19
	v_fma_f32 v18, v14, v18, v14
	v_fma_f32 v19, v15, v19, v15
	v_mul_f32_e32 v18, 0xbfcc422a, v18
	v_mul_f32_e32 v19, 0xbfcc422a, v19
	v_mul_f32_e32 v18, 0x3fb8aa3b, v18
	v_mul_f32_e32 v19, 0x3fb8aa3b, v19
	v_exp_f32_e32 v18, v18
	v_exp_f32_e32 v19, v19
	v_add_f32_e32 v18, 1.0, v18
	v_add_f32_e32 v19, 1.0, v19
	v_rcp_f32_e32 v18, v18
	v_rcp_f32_e32 v19, v19
	s_nop 0
	v_pk_mul_f32 v[14:15], v[14:15], v[18:19]
	v_cvt_pk_bf16_f32 v18, v12, v13
	v_lshlrev_b32_e32 v12, 10, v26
	v_mov_b32_e32 v13, v135
	v_cvt_pk_bf16_f32 v19, v14, v15
	v_lshl_add_u64 v[14:15], v[64:65], 0, v[12:13]
	v_lshl_add_u64 v[14:15], v[14:15], 0, v[62:63]
	global_store_dwordx2 v[14:15], v[18:19], off
	v_lshl_add_u64 v[14:15], v[66:67], 0, v[16:17]
	v_lshl_add_u64 v[14:15], v[14:15], 0, v[134:135]
	s_waitcnt vmcnt(15)
; DI float bf2f(unsigned short h) { return __uint_as_float(((unsigned)h) << 16); }
; DI uint2 pk4(f32x4 v) { return make_uint2(pk2(v[0], v[1]), pk2(v[2], v[3])); }
; DI float gelu_t(float x) { float u = 1.5957691216057308f * (x + 0.044715f * x * x * x); return x * __builtin_amdgcn_rcpf(1.f + __expf(-u)); }
; DI void phase5(const Params& p, unsigned char* smem, const int tid, const int vb, const int nvb) {
;     ...
;         epi_loop(acc, tid, [&](const int epi_f, const int epi_t, const f32x4 accv) __attribute__((always_inline)) {
;             const int m = mt * 128 + epi_f, n = nt * 128 + epi_t;
;             const int t = m >> 4, c = m & 15;
;             const size_t tok = (size_t)n * 64 + t;
;             const int ch = g * 16 + c;
;             uint2 uu = *(const uint2*)(us + (((size_t)g * 512 + n) * 64 + t) * 16 + c);
;             float4 dd = *(const float4*)(dsk + ch);
;             f32x4 v = accv;
;             v[0] = gelu_t(v[0] + dd.x * bf2f(uu.x & 0xffff));
;             v[1] = gelu_t(v[1] + dd.y * bf2f(uu.x >> 16));
;             v[2] = gelu_t(v[2] + dd.z * bf2f(uu.y & 0xffff));
;             v[3] = gelu_t(v[3] + dd.w * bf2f(uu.y >> 16));
;             *(uint2*)(ys + tok * 512 + ch) = pk4(v);
	v_mov_b64_e32 v[14:15], v[236:237]
	v_lshlrev_b32_e32 v22, 16, v14
	v_and_b32_e32 v23, 0xffff0000, v14
	v_mov_b64_e32 v[18:19], v[242:243]
	v_mov_b64_e32 v[20:21], v[244:245]
	v_pk_fma_f32 v[8:9], v[18:19], v[22:23], v[8:9]
	s_nop 0
	v_mul_f32_e32 v14, 0x3d372713, v8
	v_mul_f32_e32 v14, v8, v14
	v_fma_f32 v14, v8, v14, v8
	v_mul_f32_e32 v14, 0xbfcc422a, v14
	v_mul_f32_e32 v14, 0x3fb8aa3b, v14
	v_exp_f32_e32 v14, v14
	s_nop 0
	v_add_f32_e32 v14, 1.0, v14
	v_rcp_f32_e32 v18, v14
	v_mul_f32_e32 v14, 0x3d372713, v9
	v_mul_f32_e32 v14, v9, v14
	v_fma_f32 v14, v9, v14, v9
	v_mul_f32_e32 v14, 0xbfcc422a, v14
	v_mul_f32_e32 v14, 0x3fb8aa3b, v14
	v_exp_f32_e32 v14, v14
	s_nop 0
	v_add_f32_e32 v14, 1.0, v14
	v_rcp_f32_e32 v19, v14
	v_lshlrev_b32_e32 v14, 16, v15
	v_and_b32_e32 v15, 0xffff0000, v15
	v_pk_fma_f32 v[10:11], v[20:21], v[14:15], v[10:11]
	v_pk_mul_f32 v[8:9], v[8:9], v[18:19]
	v_mul_f32_e32 v14, 0x3d372713, v10
	v_mul_f32_e32 v15, 0x3d372713, v11
	v_mul_f32_e32 v14, v10, v14
	v_mul_f32_e32 v15, v11, v15
	v_fma_f32 v14, v10, v14, v10
	v_fma_f32 v15, v11, v15, v11
	v_mul_f32_e32 v14, 0xbfcc422a, v14
	v_mul_f32_e32 v15, 0xbfcc422a, v15
	v_mul_f32_e32 v14, 0x3fb8aa3b, v14
	v_mul_f32_e32 v15, 0x3fb8aa3b, v15
	v_exp_f32_e32 v14, v14
	v_exp_f32_e32 v15, v15
	v_cvt_pk_bf16_f32 v8, v8, v9
	v_add_f32_e32 v14, 1.0, v14
	v_add_f32_e32 v15, 1.0, v15
	v_rcp_f32_e32 v14, v14
	v_rcp_f32_e32 v15, v15
	s_nop 0
	v_pk_mul_f32 v[10:11], v[10:11], v[14:15]
	s_nop 0
	v_cvt_pk_bf16_f32 v9, v10, v11
	v_lshl_add_u64 v[10:11], v[56:57], 0, v[12:13]
	v_lshl_add_u64 v[10:11], v[10:11], 0, v[62:63]
	global_store_dwordx2 v[10:11], v[8:9], off
	v_lshl_add_u64 v[8:9], v[58:59], 0, v[16:17]
	v_lshl_add_u64 v[8:9], v[8:9], 0, v[134:135]
	s_waitcnt vmcnt(15)
	v_mov_b64_e32 v[14:15], v[238:239]
	v_lshlrev_b32_e32 v18, 16, v14
	v_and_b32_e32 v19, 0xffff0000, v14
	v_mov_b64_e32 v[8:9], v[242:243]
	v_mov_b64_e32 v[10:11], v[244:245]
	v_pk_fma_f32 v[4:5], v[8:9], v[18:19], v[4:5]
	s_nop 0
	v_mul_f32_e32 v8, 0x3d372713, v4
	v_mul_f32_e32 v9, 0x3d372713, v5
	v_mul_f32_e32 v8, v4, v8
	v_mul_f32_e32 v9, v5, v9
	v_fma_f32 v8, v4, v8, v4
	v_fma_f32 v9, v5, v9, v5
	v_mul_f32_e32 v8, 0xbfcc422a, v8
	v_mul_f32_e32 v9, 0xbfcc422a, v9
	v_mul_f32_e32 v8, 0x3fb8aa3b, v8
	v_mul_f32_e32 v9, 0x3fb8aa3b, v9
	v_exp_f32_e32 v8, v8
	v_exp_f32_e32 v9, v9
	v_add_f32_e32 v8, 1.0, v8
	v_add_f32_e32 v9, 1.0, v9
	v_rcp_f32_e32 v8, v8
	v_rcp_f32_e32 v9, v9
	s_nop 0
	v_pk_mul_f32 v[4:5], v[4:5], v[8:9]
	v_lshlrev_b32_e32 v8, 16, v15
	v_and_b32_e32 v9, 0xffff0000, v15
	v_pk_fma_f32 v[6:7], v[10:11], v[8:9], v[6:7]
	v_cvt_pk_bf16_f32 v4, v4, v5
	v_mul_f32_e32 v8, 0x3d372713, v6
	v_mul_f32_e32 v9, 0x3d372713, v7
	v_mul_f32_e32 v8, v6, v8
	v_mul_f32_e32 v9, v7, v9
	v_fma_f32 v8, v6, v8, v6
	v_fma_f32 v9, v7, v9, v7
	v_mul_f32_e32 v8, 0xbfcc422a, v8
	v_mul_f32_e32 v9, 0xbfcc422a, v9
	v_mul_f32_e32 v8, 0x3fb8aa3b, v8
	v_mul_f32_e32 v9, 0x3fb8aa3b, v9
	v_exp_f32_e32 v8, v8
	v_exp_f32_e32 v9, v9
	v_add_f32_e32 v8, 1.0, v8
	v_add_f32_e32 v9, 1.0, v9
	v_rcp_f32_e32 v8, v8
	v_rcp_f32_e32 v9, v9
	s_nop 0
	v_pk_mul_f32 v[6:7], v[6:7], v[8:9]
	s_nop 0
	v_cvt_pk_bf16_f32 v5, v6, v7
	v_lshl_add_u64 v[6:7], v[52:53], 0, v[12:13]
	v_lshl_add_u64 v[6:7], v[6:7], 0, v[62:63]
	global_store_dwordx2 v[6:7], v[4:5], off
	v_lshl_add_u64 v[4:5], v[54:55], 0, v[16:17]
	v_lshl_add_u64 v[4:5], v[4:5], 0, v[134:135]
	s_waitcnt vmcnt(15)
	v_mov_b64_e32 v[8:9], v[240:241]
	v_lshlrev_b32_e32 v10, 16, v8
	v_and_b32_e32 v11, 0xffff0000, v8
	v_mov_b64_e32 v[4:5], v[242:243]
	v_mov_b64_e32 v[6:7], v[244:245]
	v_pk_fma_f32 v[0:1], v[4:5], v[10:11], v[0:1]
	s_nop 0
	v_mul_f32_e32 v4, 0x3d372713, v0
	v_mul_f32_e32 v5, 0x3d372713, v1
	v_mul_f32_e32 v4, v0, v4
	v_mul_f32_e32 v5, v1, v5
	v_fma_f32 v4, v0, v4, v0
	v_fma_f32 v5, v1, v5, v1
	v_mul_f32_e32 v4, 0xbfcc422a, v4
	v_mul_f32_e32 v5, 0xbfcc422a, v5
	v_mul_f32_e32 v4, 0x3fb8aa3b, v4
	v_mul_f32_e32 v5, 0x3fb8aa3b, v5
	v_exp_f32_e32 v4, v4
	v_exp_f32_e32 v5, v5
	v_add_f32_e32 v4, 1.0, v4
	v_add_f32_e32 v5, 1.0, v5
	v_rcp_f32_e32 v4, v4
	v_rcp_f32_e32 v5, v5
	s_nop 0
	v_pk_mul_f32 v[0:1], v[0:1], v[4:5]
	v_lshlrev_b32_e32 v4, 16, v9
	v_and_b32_e32 v5, 0xffff0000, v9
	v_pk_fma_f32 v[2:3], v[6:7], v[4:5], v[2:3]
	v_cvt_pk_bf16_f32 v0, v0, v1
	v_mul_f32_e32 v4, 0x3d372713, v2
	v_mul_f32_e32 v5, 0x3d372713, v3
	v_mul_f32_e32 v4, v2, v4
	v_mul_f32_e32 v5, v3, v5
	v_fma_f32 v4, v2, v4, v2
	v_fma_f32 v5, v3, v5, v3
	v_mul_f32_e32 v4, 0xbfcc422a, v4
	v_mul_f32_e32 v5, 0xbfcc422a, v5
	v_mul_f32_e32 v4, 0x3fb8aa3b, v4
	v_mul_f32_e32 v5, 0x3fb8aa3b, v5
	v_exp_f32_e32 v4, v4
	v_exp_f32_e32 v5, v5
	v_add_f32_e32 v4, 1.0, v4
	v_add_f32_e32 v5, 1.0, v5
	v_rcp_f32_e32 v4, v4
	v_rcp_f32_e32 v5, v5
	s_nop 0
	v_pk_mul_f32 v[2:3], v[2:3], v[4:5]
	s_nop 0
	v_cvt_pk_bf16_f32 v1, v2, v3
	v_lshl_add_u64 v[2:3], v[48:49], 0, v[12:13]
	v_lshl_add_u64 v[2:3], v[2:3], 0, v[62:63]
	global_store_dwordx2 v[2:3], v[0:1], off
	s_andn2_b64 exec, exec, s[14:15]
	s_cbranch_execz .LBB0_573
